# P0 adaLN GEMV k-loop software-pipelined (next 8 weight loads in flight while current step is consumed)
# speedup vs baseline: 1.0165x; 1.0029x over previous
; __global__ void __launch_bounds__(512, 2) fwd_megakernel(Params p) {
;     ...
;         const int col = cgp * 512 + tid;
;         float a0 = 0.f, a1 = 0.f, a2 = 0.f, a3 = 0.f, a4 = 0.f;
;         const float* wp = p.w_mod + (size_t)(kc * 128) * 6144 + col;
; #pragma unroll 8
;         for (int k = 0; k < 128; ++k) { const float w = wp[(size_t)k * 6144]; a0 += sl[k] * w; a1 += sl[128 + k] * w; a2 += sl[256 + k] * w; a3 += sl[384 + k] * w; a4 += sl[512 + k] * w; }
;         if (kc == 0) { const float bm = p.b_mod[col]; a0 += bm; a1 += bm; a2 += bm; a3 += bm; a4 += bm; }
.LBB0_31:
	s_or_b64 exec, exec, s[8:9]
	s_mul_i32 s19, s19, 12
	s_sub_i32 s0, s92, s19
	s_mul_hi_i32 s1, s18, 0x6000
	s_mulk_i32 s18, 0x6000
	s_waitcnt lgkmcnt(0)
	v_lshl_add_u32 v4, s0, 9, v2
	s_add_u32 s0, s46, s18
	s_addc_u32 s1, s47, s1
	v_ashrrev_i32_e32 v5, 31, v4
	v_mov_b32_e32 v3, 0
	s_movk_i32 s4, 0x6000
	v_lshl_add_u64 v[10:11], v[4:5], 2, s[0:1]
	s_mov_b64 s[0:1], 0
	s_mov_b32 s5, 0
	s_mov_b32 s6, 0xc000
	s_mov_b32 s7, 0x12000
	s_mov_b32 s8, 0x18000
	s_mov_b32 s9, 0x1e000
	s_mov_b32 s10, 0x24000
	s_mov_b32 s11, 0x2a000
	v_mov_b32_e32 v6, 0
	v_mov_b32_e32 v7, v3
	v_mov_b32_e32 v8, 0
	v_mov_b32_e32 v9, v3
	s_barrier
	v_add_co_u32_e32 v88, vcc, s4, v10
	s_nop 1
	v_addc_co_u32_e32 v89, vcc, 0, v11, vcc
	v_add_co_u32_e32 v90, vcc, s6, v10
	s_nop 1
	v_addc_co_u32_e32 v91, vcc, 0, v11, vcc
	v_add_co_u32_e32 v92, vcc, s7, v10
	s_nop 1
	v_addc_co_u32_e32 v93, vcc, 0, v11, vcc
	v_add_co_u32_e32 v94, vcc, s8, v10
	s_nop 1
	v_addc_co_u32_e32 v95, vcc, 0, v11, vcc
	v_add_co_u32_e32 v96, vcc, s9, v10
	s_nop 1
	v_addc_co_u32_e32 v97, vcc, 0, v11, vcc
	v_add_co_u32_e32 v98, vcc, s10, v10
	s_nop 1
	v_addc_co_u32_e32 v99, vcc, 0, v11, vcc
	v_add_co_u32_e32 v100, vcc, s11, v10
	s_nop 1
	v_addc_co_u32_e32 v101, vcc, 0, v11, vcc
	v_lshl_add_u64 v[102:103], v[10:11], 0, s[0:1]
	global_load_dword v52, v[102:103], off
	v_lshl_add_u64 v[102:103], v[88:89], 0, s[0:1]
	global_load_dword v54, v[102:103], off
	v_lshl_add_u64 v[102:103], v[90:91], 0, s[0:1]
	global_load_dword v56, v[102:103], off
	v_lshl_add_u64 v[102:103], v[92:93], 0, s[0:1]
	global_load_dword v58, v[102:103], off
	v_lshl_add_u64 v[102:103], v[94:95], 0, s[0:1]
	global_load_dword v60, v[102:103], off
	v_lshl_add_u64 v[102:103], v[96:97], 0, s[0:1]
	global_load_dword v62, v[102:103], off
	v_lshl_add_u64 v[102:103], v[98:99], 0, s[0:1]
	global_load_dword v64, v[102:103], off
	v_lshl_add_u64 v[102:103], v[100:101], 0, s[0:1]
	global_load_dword v66, v[102:103], off
	s_add_u32 s0, s0, 0x30000
	s_addc_u32 s1, s1, 0
.Lmy_gemv_loop:
	v_lshl_add_u64 v[102:103], v[10:11], 0, s[0:1]
	global_load_dword v70, v[102:103], off
	v_lshl_add_u64 v[102:103], v[88:89], 0, s[0:1]
	global_load_dword v72, v[102:103], off
	v_lshl_add_u64 v[102:103], v[90:91], 0, s[0:1]
	global_load_dword v74, v[102:103], off
	v_lshl_add_u64 v[102:103], v[92:93], 0, s[0:1]
	global_load_dword v76, v[102:103], off
	v_lshl_add_u64 v[102:103], v[94:95], 0, s[0:1]
	global_load_dword v78, v[102:103], off
	v_lshl_add_u64 v[102:103], v[96:97], 0, s[0:1]
	global_load_dword v80, v[102:103], off
	v_lshl_add_u64 v[102:103], v[98:99], 0, s[0:1]
	global_load_dword v82, v[102:103], off
	v_lshl_add_u64 v[102:103], v[100:101], 0, s[0:1]
	global_load_dword v84, v[102:103], off
	s_add_u32 s0, s0, 0x30000
	s_addc_u32 s1, s1, 0
	v_mov_b32_e32 v48, s5
	ds_read_b128 v[12:15], v48 offset:512
	ds_read_b128 v[16:19], v48 offset:528
	ds_read_b128 v[20:23], v48 offset:1024
	ds_read_b128 v[24:27], v48 offset:1040
	ds_read_b128 v[28:31], v48 offset:1536
	ds_read_b128 v[32:35], v48 offset:1552
	ds_read_b128 v[36:39], v48 offset:2048
	ds_read_b128 v[40:43], v48 offset:2064
	ds_read_b128 v[44:47], v48
	ds_read_b128 v[48:51], v48 offset:16
	s_waitcnt lgkmcnt(7)
	v_mov_b32_e32 v68, v20
	v_mov_b32_e32 v69, v12
	v_mov_b32_e32 v12, v21
	v_mov_b32_e32 v20, v22
	v_mov_b32_e32 v21, v14
	v_mov_b32_e32 v14, v23
	s_waitcnt lgkmcnt(3)
	v_mov_b32_e32 v22, v36
	v_mov_b32_e32 v23, v28
	v_mov_b32_e32 v28, v37
	v_mov_b32_e32 v36, v38
	v_mov_b32_e32 v37, v30
	v_mov_b32_e32 v30, v39
	v_mov_b32_e32 v38, v24
	v_mov_b32_e32 v39, v16
	v_mov_b32_e32 v16, v25
	v_mov_b32_e32 v24, v26
	v_mov_b32_e32 v25, v18
	v_mov_b32_e32 v18, v27
	s_waitcnt lgkmcnt(2)
	v_mov_b32_e32 v26, v40
	v_mov_b32_e32 v27, v32
	v_mov_b32_e32 v32, v41
	v_mov_b32_e32 v40, v42
	v_mov_b32_e32 v41, v34
	v_mov_b32_e32 v34, v43
	s_waitcnt vmcnt(15)
	v_pk_fma_f32 v[8:9], v[52:53], v[68:69], v[8:9] op_sel_hi:[0,1,1]
	v_pk_fma_f32 v[6:7], v[52:53], v[22:23], v[6:7] op_sel_hi:[0,1,1]
	s_waitcnt lgkmcnt(1)
	v_fmac_f32_e32 v3, v52, v44
	s_waitcnt vmcnt(14)
	v_fmac_f32_e32 v3, v54, v45
	v_pk_fma_f32 v[8:9], v[54:55], v[12:13], v[8:9] op_sel_hi:[0,1,1]
	v_pk_fma_f32 v[6:7], v[54:55], v[28:29], v[6:7] op_sel_hi:[0,1,1]
	s_waitcnt vmcnt(13)
	v_fmac_f32_e32 v3, v56, v46
	v_pk_fma_f32 v[8:9], v[56:57], v[20:21], v[8:9] op_sel_hi:[0,1,1]
	v_pk_fma_f32 v[6:7], v[56:57], v[36:37], v[6:7] op_sel_hi:[0,1,1]
	s_waitcnt vmcnt(12)
	v_fmac_f32_e32 v3, v58, v47
	v_pk_fma_f32 v[8:9], v[58:59], v[14:15], v[8:9] op_sel_hi:[0,1,1]
	v_pk_fma_f32 v[6:7], v[58:59], v[30:31], v[6:7] op_sel_hi:[0,1,1]
	s_waitcnt vmcnt(11) lgkmcnt(0)
	v_fmac_f32_e32 v3, v60, v48
	v_pk_fma_f32 v[8:9], v[60:61], v[38:39], v[8:9] op_sel_hi:[0,1,1]
	v_pk_fma_f32 v[6:7], v[60:61], v[26:27], v[6:7] op_sel_hi:[0,1,1]
	s_waitcnt vmcnt(10)
	v_fmac_f32_e32 v3, v62, v49
	v_pk_fma_f32 v[8:9], v[62:63], v[16:17], v[8:9] op_sel_hi:[0,1,1]
	v_pk_fma_f32 v[6:7], v[62:63], v[32:33], v[6:7] op_sel_hi:[0,1,1]
	s_waitcnt vmcnt(9)
	v_fmac_f32_e32 v3, v64, v50
	v_pk_fma_f32 v[8:9], v[64:65], v[24:25], v[8:9] op_sel_hi:[0,1,1]
	v_pk_fma_f32 v[6:7], v[64:65], v[40:41], v[6:7] op_sel_hi:[0,1,1]
	s_waitcnt vmcnt(8)
	v_fmac_f32_e32 v3, v66, v51
	v_pk_fma_f32 v[8:9], v[66:67], v[18:19], v[8:9] op_sel_hi:[0,1,1]
	v_pk_fma_f32 v[6:7], v[66:67], v[34:35], v[6:7] op_sel_hi:[0,1,1]
	s_add_i32 s5, s5, 32
	s_cmp_eq_u32 s0, 0x300000
	s_cbranch_scc1 .Lmy_gemv_last
; __global__ void __launch_bounds__(512, 2) fwd_megakernel(Params p) {
;     ...
; #pragma unroll 8
;         for (int k = 0; k < 128; ++k) { const float w = wp[(size_t)k * 6144]; a0 += sl[k] * w; a1 += sl[128 + k] * w; a2 += sl[256 + k] * w; a3 += sl[384 + k] * w; a4 += sl[512 + k] * w; }
;         if (kc == 0) { const float bm = p.b_mod[col]; a0 += bm; a1 += bm; a2 += bm; a3 += bm; a4 += bm; }
	v_lshl_add_u64 v[102:103], v[10:11], 0, s[0:1]
	global_load_dword v52, v[102:103], off
	v_lshl_add_u64 v[102:103], v[88:89], 0, s[0:1]
	global_load_dword v54, v[102:103], off
	v_lshl_add_u64 v[102:103], v[90:91], 0, s[0:1]
	global_load_dword v56, v[102:103], off
	v_lshl_add_u64 v[102:103], v[92:93], 0, s[0:1]
	global_load_dword v58, v[102:103], off
	v_lshl_add_u64 v[102:103], v[94:95], 0, s[0:1]
	global_load_dword v60, v[102:103], off
	v_lshl_add_u64 v[102:103], v[96:97], 0, s[0:1]
	global_load_dword v62, v[102:103], off
	v_lshl_add_u64 v[102:103], v[98:99], 0, s[0:1]
	global_load_dword v64, v[102:103], off
	v_lshl_add_u64 v[102:103], v[100:101], 0, s[0:1]
	global_load_dword v66, v[102:103], off
	s_add_u32 s0, s0, 0x30000
	s_addc_u32 s1, s1, 0
	v_mov_b32_e32 v48, s5
	ds_read_b128 v[12:15], v48 offset:512
	ds_read_b128 v[16:19], v48 offset:528
	ds_read_b128 v[20:23], v48 offset:1024
	ds_read_b128 v[24:27], v48 offset:1040
	ds_read_b128 v[28:31], v48 offset:1536
	ds_read_b128 v[32:35], v48 offset:1552
	ds_read_b128 v[36:39], v48 offset:2048
	ds_read_b128 v[40:43], v48 offset:2064
	ds_read_b128 v[44:47], v48
	ds_read_b128 v[48:51], v48 offset:16
	s_waitcnt lgkmcnt(7)
	v_mov_b32_e32 v68, v20
	v_mov_b32_e32 v69, v12
	v_mov_b32_e32 v12, v21
	v_mov_b32_e32 v20, v22
	v_mov_b32_e32 v21, v14
	v_mov_b32_e32 v14, v23
	s_waitcnt lgkmcnt(3)
	v_mov_b32_e32 v22, v36
	v_mov_b32_e32 v23, v28
	v_mov_b32_e32 v28, v37
	v_mov_b32_e32 v36, v38
	v_mov_b32_e32 v37, v30
	v_mov_b32_e32 v30, v39
	v_mov_b32_e32 v38, v24
	v_mov_b32_e32 v39, v16
	v_mov_b32_e32 v16, v25
	v_mov_b32_e32 v24, v26
	v_mov_b32_e32 v25, v18
	v_mov_b32_e32 v18, v27
	s_waitcnt lgkmcnt(2)
	v_mov_b32_e32 v26, v40
	v_mov_b32_e32 v27, v32
	v_mov_b32_e32 v32, v41
	v_mov_b32_e32 v40, v42
	v_mov_b32_e32 v41, v34
	v_mov_b32_e32 v34, v43
	s_waitcnt vmcnt(15)
	v_pk_fma_f32 v[8:9], v[70:71], v[68:69], v[8:9] op_sel_hi:[0,1,1]
	v_pk_fma_f32 v[6:7], v[70:71], v[22:23], v[6:7] op_sel_hi:[0,1,1]
	s_waitcnt lgkmcnt(1)
	v_fmac_f32_e32 v3, v70, v44
	s_waitcnt vmcnt(14)
	v_fmac_f32_e32 v3, v72, v45
	v_pk_fma_f32 v[8:9], v[72:73], v[12:13], v[8:9] op_sel_hi:[0,1,1]
	v_pk_fma_f32 v[6:7], v[72:73], v[28:29], v[6:7] op_sel_hi:[0,1,1]
	s_waitcnt vmcnt(13)
	v_fmac_f32_e32 v3, v74, v46
	v_pk_fma_f32 v[8:9], v[74:75], v[20:21], v[8:9] op_sel_hi:[0,1,1]
	v_pk_fma_f32 v[6:7], v[74:75], v[36:37], v[6:7] op_sel_hi:[0,1,1]
	s_waitcnt vmcnt(12)
	v_fmac_f32_e32 v3, v76, v47
	v_pk_fma_f32 v[8:9], v[76:77], v[14:15], v[8:9] op_sel_hi:[0,1,1]
	v_pk_fma_f32 v[6:7], v[76:77], v[30:31], v[6:7] op_sel_hi:[0,1,1]
	s_waitcnt vmcnt(11) lgkmcnt(0)
	v_fmac_f32_e32 v3, v78, v48
	v_pk_fma_f32 v[8:9], v[78:79], v[38:39], v[8:9] op_sel_hi:[0,1,1]
	v_pk_fma_f32 v[6:7], v[78:79], v[26:27], v[6:7] op_sel_hi:[0,1,1]
	s_waitcnt vmcnt(10)
	v_fmac_f32_e32 v3, v80, v49
	v_pk_fma_f32 v[8:9], v[80:81], v[16:17], v[8:9] op_sel_hi:[0,1,1]
	v_pk_fma_f32 v[6:7], v[80:81], v[32:33], v[6:7] op_sel_hi:[0,1,1]
	s_waitcnt vmcnt(9)
	v_fmac_f32_e32 v3, v82, v50
	v_pk_fma_f32 v[8:9], v[82:83], v[24:25], v[8:9] op_sel_hi:[0,1,1]
	v_pk_fma_f32 v[6:7], v[82:83], v[40:41], v[6:7] op_sel_hi:[0,1,1]
	s_waitcnt vmcnt(8)
	v_fmac_f32_e32 v3, v84, v51
	v_pk_fma_f32 v[8:9], v[84:85], v[18:19], v[8:9] op_sel_hi:[0,1,1]
	v_pk_fma_f32 v[6:7], v[84:85], v[34:35], v[6:7] op_sel_hi:[0,1,1]
	s_add_i32 s5, s5, 32
	s_branch .Lmy_gemv_loop
.Lmy_gemv_last:
	v_mov_b32_e32 v48, s5
	ds_read_b128 v[12:15], v48 offset:512
	ds_read_b128 v[16:19], v48 offset:528
	ds_read_b128 v[20:23], v48 offset:1024
	ds_read_b128 v[24:27], v48 offset:1040
	ds_read_b128 v[28:31], v48 offset:1536
	ds_read_b128 v[32:35], v48 offset:1552
	ds_read_b128 v[36:39], v48 offset:2048
	ds_read_b128 v[40:43], v48 offset:2064
	ds_read_b128 v[44:47], v48
	ds_read_b128 v[48:51], v48 offset:16
	s_waitcnt lgkmcnt(7)
	v_mov_b32_e32 v68, v20
	v_mov_b32_e32 v69, v12
	v_mov_b32_e32 v12, v21
	v_mov_b32_e32 v20, v22
	v_mov_b32_e32 v21, v14
	v_mov_b32_e32 v14, v23
	s_waitcnt lgkmcnt(3)
	v_mov_b32_e32 v22, v36
	v_mov_b32_e32 v23, v28
	v_mov_b32_e32 v28, v37
	v_mov_b32_e32 v36, v38
	v_mov_b32_e32 v37, v30
	v_mov_b32_e32 v30, v39
	v_mov_b32_e32 v38, v24
	v_mov_b32_e32 v39, v16
	v_mov_b32_e32 v16, v25
	v_mov_b32_e32 v24, v26
	v_mov_b32_e32 v25, v18
	v_mov_b32_e32 v18, v27
	s_waitcnt lgkmcnt(2)
	v_mov_b32_e32 v26, v40
	v_mov_b32_e32 v27, v32
	v_mov_b32_e32 v32, v41
	v_mov_b32_e32 v40, v42
	v_mov_b32_e32 v41, v34
	v_mov_b32_e32 v34, v43
	s_waitcnt vmcnt(7)
	v_pk_fma_f32 v[8:9], v[70:71], v[68:69], v[8:9] op_sel_hi:[0,1,1]
	v_pk_fma_f32 v[6:7], v[70:71], v[22:23], v[6:7] op_sel_hi:[0,1,1]
	s_waitcnt lgkmcnt(1)
	v_fmac_f32_e32 v3, v70, v44
	s_waitcnt vmcnt(6)
	v_fmac_f32_e32 v3, v72, v45
	v_pk_fma_f32 v[8:9], v[72:73], v[12:13], v[8:9] op_sel_hi:[0,1,1]
	v_pk_fma_f32 v[6:7], v[72:73], v[28:29], v[6:7] op_sel_hi:[0,1,1]
	s_waitcnt vmcnt(5)
	v_fmac_f32_e32 v3, v74, v46
	v_pk_fma_f32 v[8:9], v[74:75], v[20:21], v[8:9] op_sel_hi:[0,1,1]
	v_pk_fma_f32 v[6:7], v[74:75], v[36:37], v[6:7] op_sel_hi:[0,1,1]
	s_waitcnt vmcnt(4)
	v_fmac_f32_e32 v3, v76, v47
	v_pk_fma_f32 v[8:9], v[76:77], v[14:15], v[8:9] op_sel_hi:[0,1,1]
	v_pk_fma_f32 v[6:7], v[76:77], v[30:31], v[6:7] op_sel_hi:[0,1,1]
	s_waitcnt vmcnt(3) lgkmcnt(0)
	v_fmac_f32_e32 v3, v78, v48
	v_pk_fma_f32 v[8:9], v[78:79], v[38:39], v[8:9] op_sel_hi:[0,1,1]
	v_pk_fma_f32 v[6:7], v[78:79], v[26:27], v[6:7] op_sel_hi:[0,1,1]
	s_waitcnt vmcnt(2)
	v_fmac_f32_e32 v3, v80, v49
	v_pk_fma_f32 v[8:9], v[80:81], v[16:17], v[8:9] op_sel_hi:[0,1,1]
	v_pk_fma_f32 v[6:7], v[80:81], v[32:33], v[6:7] op_sel_hi:[0,1,1]
	s_waitcnt vmcnt(1)
	v_fmac_f32_e32 v3, v82, v50
	v_pk_fma_f32 v[8:9], v[82:83], v[24:25], v[8:9] op_sel_hi:[0,1,1]
	v_pk_fma_f32 v[6:7], v[82:83], v[40:41], v[6:7] op_sel_hi:[0,1,1]
	s_waitcnt vmcnt(0)
	v_fmac_f32_e32 v3, v84, v51
	v_pk_fma_f32 v[8:9], v[84:85], v[18:19], v[8:9] op_sel_hi:[0,1,1]
	v_pk_fma_f32 v[6:7], v[84:85], v[34:35], v[6:7] op_sel_hi:[0,1,1]
	s_add_i32 s5, s5, 32
	s_add_i32 s0, s92, 11
	s_cmp_lt_u32 s0, 23
	s_cbranch_scc0 .LBB0_35
	v_mov_b32_e32 v10, s48
	v_mov_b32_e32 v11, s49
	v_lshl_add_u64 v[10:11], v[4:5], 2, v[10:11]
	global_load_dword v10, v[10:11], off
	s_waitcnt vmcnt(0)
	v_add_f32_e32 v3, v3, v10
	v_pk_add_f32 v[8:9], v[8:9], v[10:11] op_sel_hi:[1,0]
	v_pk_add_f32 v[6:7], v[6:7], v[10:11] op_sel_hi:[1,0]
